# c2 + static s_setprio 1 for waves 0-3 during the attention phase
# speedup vs baseline: 1.0122x; 1.0056x over previous
; __global__ void __launch_bounds__(512, 2) fwd_mega(Args a) {
;     ...
;         } break;
;         case 6:
;             att::phase(U1, U2, U3, U0, (const float*)(ws + WS_CS), (const int*)(ws + WS_JLO), ldc, wv);
;             break;
.LBB0_198:
	v_readfirstlane_b32 s98, v217
	s_lshr_b32 s98, s98, 6
	s_cmp_lt_u32 s98, 4
	s_cbranch_scc0 .Lmy_att_prio
	s_setprio 1

; __global__ void __launch_bounds__(512, 2) fwd_mega(Args a) {
;     ...
;         } break;
;         case 6:
;             att::phase(U1, U2, U3, U0, (const float*)(ws + WS_CS), (const int*)(ws + WS_JLO), ldc, wv);
;             break;
.LBB0_377:
	s_setprio 0
	s_mov_b64 s[4:5], 0
